# ssd_scan chunk loop post-barrier part rewritten: 4 straight-line per-lt paths, batched LDS reads with counted lgkmcnt, cvt_pk packs, redundant s_loads removed
# speedup vs baseline: 1.0114x; 1.0039x over previous
; #define LAS __attribute__((address_space(3)))
; __device__ __forceinline__ unsigned pk2(float lo, float hi) { return f2bf(lo) | (f2bf(hi) << 16); }
; #define SSD_CS(buf_) do { if (w == 0) { float a = rdt * Ah; \
;             _Pragma("unroll") for (int o = 1; o < 64; o <<= 1) { const float v = __shfl_up(a, o); if (lane >= o) a += v; } \
;             ((LAS float*)(L + SS_CS))[(buf_) * 64 + lane] = a; ((LAS float*)(L + SS_DTS))[(buf_) * 64 + lane] = rdt; } } while (0)
; #define SSD_LDT(t0_) do { if (w == 0) rdt = DT[((size_t)b * SEQ + (t0_) + lane) * 64 + h]; } while (0)
; __device__ __forceinline__ void ssd_scan_mfma(const Ctx& c, bf16* X2, const float* DT, const float* a_log, const float* dskip, bool do_store) {
;     ...
;         SSD_LOAD(0); SSD_LDT(0); SSD_CS(0); SSD_LDT(64);
;         for (int ch = 0; ch < SEQ / 64; ++ch) {
;             const int t0 = ch * 64, cb = ch & 1; LAS float* CS = (LAS float*)(L + SS_CS) + cb * 64; LAS float* DTS = (LAS float*)(L + SS_DTS) + cb * 64;
;             LAS unsigned char* SBr = L + SS_SB + cb * 17408; LAS unsigned char* SBw = L + SS_SB + (cb ^ 1) * 17408;
;             __syncthreads();
; #pragma unroll
;             for (int e = 0; e < 2; ++e) { const int cc = tid + 512 * e;
;                 *(LAS v4u*)(L + SS_B + (cc >> 4) * 272 + (cc & 15) * 16) = rB[e]; *(LAS v4u*)(L + SS_C + (cc >> 4) * 272 + (cc & 15) * 16) = rC[e]; }
;             *(LAS v4u*)(L + SS_XR + (tid >> 3) * 144 + (tid & 7) * 16) = rXR;
;             { const int sr = tid >> 3, p8 = tid & 7; const float fd = DTS[sr], fw = fd * __expf(CS[63] - CS[sr]);
;               float xv[8];
; #pragma unroll
;               for (int j = 0; j < 4; ++j) { xv[2 * j] = bflo(rXR[j]); xv[2 * j + 1] = bfhi(rXR[j]); }
;               v4u o1, o2; o1.x = pk2(xv[0] * fd, xv[1] * fd); o1.y = pk2(xv[2] * fd, xv[3] * fd); o1.z = pk2(xv[4] * fd, xv[5] * fd); o1.w = pk2(xv[6] * fd, xv[7] * fd);
;               o2.x = pk2(xv[0] * fw, xv[1] * fw); o2.y = pk2(xv[2] * fw, xv[3] * fw); o2.z = pk2(xv[4] * fw, xv[5] * fw); o2.w = pk2(xv[6] * fw, xv[7] * fw);
;               *(LAS v4u*)(L + SS_XD + sr * 144 + p8 * 16) = o1; *(LAS v4u*)(L + SS_XW + sr * 144 + p8 * 16) = o2; }
;             if (ch + 1 < SEQ / 64) { SSD_LOAD(t0 + 64); SSD_CS(cb ^ 1); if (ch + 2 < SEQ / 64) SSD_LDT(t0 + 128); }
.LBB0_467:
	s_lshl_b32 s2, s54, 6
	s_and_b32 s54, s85, 63
	s_lshl_b32 s57, s54, 2
	s_and_b32 s63, s85, 56
	s_lshl_b64 s[52:53], s[52:53], 20
	s_lshl_b32 s54, s54, 7
	s_lshl_b32 s63, s63, 5
	s_or_b32 s52, s52, s57
	v_lshl_add_u64 v[96:97], s[52:53], 0, v[82:83]
	s_add_u32 s52, s54, s56
	s_addc_u32 s53, 0, s55
	v_lshl_add_u64 v[98:99], s[52:53], 0, v[84:85]
	v_lshl_add_u64 v[100:101], s[52:53], 0, v[86:87]
	s_add_u32 s52, s63, s56
	s_addc_u32 s53, 0, s55
	v_mov_b32_e32 v18, 0
	s_waitcnt vmcnt(5)
	v_mov_b32_e32 v95, v94
	v_lshl_add_u64 v[102:103], s[52:53], 0, v[88:89]
	v_lshl_add_u64 v[104:105], s[52:53], 0, v[90:91]
	s_mov_b32 s63, 0
	v_mov_b32_e32 v19, v18
	v_mov_b32_e32 v20, v18
	v_mov_b32_e32 v21, v18
	v_mov_b32_e32 v14, v18
	v_mov_b32_e32 v15, v18
	v_mov_b32_e32 v16, v18
	v_mov_b32_e32 v17, v18
	v_mov_b32_e32 v10, v18
	v_mov_b32_e32 v11, v18
	v_mov_b32_e32 v12, v18
	v_mov_b32_e32 v13, v18
	v_mov_b32_e32 v6, v18
	v_mov_b32_e32 v7, v18
	v_mov_b32_e32 v8, v18
	v_mov_b32_e32 v9, v18
	s_branch .LBB0_469
.LBB0_469:
	s_and_b32 s96, s63, 1
	s_lshl_b32 s52, s96, 8
	s_add_i32 s65, s52, 0
	s_add_i32 s65, s65, 0x17c00
	s_waitcnt lgkmcnt(0)
	s_barrier
	s_waitcnt vmcnt(4)
	ds_write_b128 v130, v[30:33]
	s_waitcnt vmcnt(3)
	ds_write_b128 v130, v[26:29] offset:17408
	s_waitcnt vmcnt(2)
	ds_write_b128 v131, v[38:41]
	s_waitcnt vmcnt(1)
	ds_write_b128 v131, v[34:37] offset:17408
	s_waitcnt vmcnt(0)
	ds_write_b128 v132, v[22:25] offset:34816
	v_add_u32_e32 v26, s52, v112
	v_mov_b32_e32 v27, s65
	v_lshl_add_u32 v28, v108, 2, s65
	ds_read_b32 v26, v26
	ds_read_b32 v27, v27 offset:252
	ds_read_b32 v28, v28
	v_lshlrev_b32_e32 v31, 16, v23
	v_lshlrev_b32_e32 v30, 16, v22
	v_and_b32_e32 v23, 0xffff0000, v23
	v_and_b32_e32 v22, 0xffff0000, v22
	s_waitcnt lgkmcnt(0)
	v_sub_f32_e32 v27, v27, v28
	v_mul_f32_e32 v27, 0x3fb8aa3b, v27
	v_exp_f32_e32 v27, v27
	v_and_b32_e32 v41, 0xffff0000, v25
	v_and_b32_e32 v40, 0xffff0000, v24
	v_lshlrev_b32_e32 v39, 16, v25
	v_mul_f32_e32 v28, v26, v27
	v_pk_mul_f32 v[34:35], v[26:27], v[22:23] op_sel_hi:[0,1]
	v_lshlrev_b32_e32 v38, 16, v24
	v_pk_mul_f32 v[24:25], v[26:27], v[40:41] op_sel_hi:[0,1]
	v_pk_mul_f32 v[32:33], v[26:27], v[30:31] op_sel_hi:[0,1]
	v_pk_mul_f32 v[30:31], v[28:29], v[30:31] op_sel_hi:[0,1]
	v_pk_mul_f32 v[36:37], v[28:29], v[22:23] op_sel_hi:[0,1]
	v_pk_mul_f32 v[22:23], v[26:27], v[38:39] op_sel_hi:[0,1]
	v_bfe_u32 v26, v25, 16, 1
	v_bfe_u32 v27, v24, 16, 1
	v_bfe_u32 v29, v35, 16, 1
	v_bfe_u32 v42, v34, 16, 1
	v_add3_u32 v34, v34, v42, s88
	v_add3_u32 v29, v35, v29, s88
	v_add3_u32 v24, v24, v27, s88
	v_add3_u32 v25, v25, v26, s88
	v_bfe_u32 v26, v32, 16, 1
	v_bfe_u32 v27, v33, 16, 1
	v_bfe_u32 v35, v22, 16, 1
	v_bfe_u32 v42, v23, 16, 1
	v_add3_u32 v23, v23, v42, s88
	v_add3_u32 v22, v22, v35, s88
	v_add3_u32 v27, v33, v27, s88
	v_add3_u32 v26, v32, v26, s88
	v_lshrrev_b32_e32 v26, 16, v26
	v_lshrrev_b32_e32 v27, 16, v27
	v_lshrrev_b32_e32 v22, 16, v22
	v_lshrrev_b32_e32 v23, 16, v23
	v_and_or_b32 v25, v25, s87, v23
	v_and_or_b32 v24, v24, s87, v22
	v_and_or_b32 v23, v29, s87, v27
	v_and_or_b32 v22, v34, s87, v26
	v_pk_mul_f32 v[26:27], v[28:29], v[38:39] op_sel_hi:[0,1]
	v_pk_mul_f32 v[28:29], v[28:29], v[40:41] op_sel_hi:[0,1]
	s_load_dwordx2 s[4:5], s[68:69], 0x120
	v_bfe_u32 v32, v29, 16, 1
	v_bfe_u32 v33, v28, 16, 1
	v_bfe_u32 v34, v37, 16, 1
	v_bfe_u32 v35, v36, 16, 1
	v_add3_u32 v35, v36, v35, s88
	v_add3_u32 v34, v37, v34, s88
	v_add3_u32 v28, v28, v33, s88
	v_add3_u32 v29, v29, v32, s88
	v_bfe_u32 v32, v30, 16, 1
	v_bfe_u32 v33, v31, 16, 1
	v_bfe_u32 v36, v26, 16, 1
	v_bfe_u32 v37, v27, 16, 1
	v_add3_u32 v27, v27, v37, s88
	v_add3_u32 v26, v26, v36, s88
	v_add3_u32 v31, v31, v33, s88
	v_add3_u32 v30, v30, v32, s88
	v_lshrrev_b32_e32 v30, 16, v30
	v_lshrrev_b32_e32 v31, 16, v31
	v_lshrrev_b32_e32 v26, 16, v26
	v_lshrrev_b32_e32 v27, 16, v27
	v_and_or_b32 v29, v29, s87, v27
	v_and_or_b32 v28, v28, s87, v26
	v_and_or_b32 v27, v34, s87, v31
	v_and_or_b32 v26, v35, s87, v30
	ds_write_b128 v132, v[22:25] offset:44032
	ds_write_b128 v132, v[26:29] offset:53248
	s_waitcnt lgkmcnt(0)
	v_lshl_add_u64 v[22:23], s[4:5], 0, v[102:103]
	s_mov_b32 s52, 0x234c2000
	v_add_co_u32_e32 v22, vcc, s52, v22
	s_xor_b32 s76, s96, 1
	s_nop 0
	v_addc_co_u32_e32 v23, vcc, 0, v23, vcc
	global_load_dwordx4 v[30:33], v[22:23], off
	global_load_dwordx4 v[26:29], v[22:23], off offset:2048
	v_lshl_add_u64 v[22:23], s[4:5], 0, v[104:105]
	v_add_co_u32_e32 v22, vcc, 0x234c2000, v22
	s_mov_b64 s[6:7], s[68:69]
	s_nop 0
	v_addc_co_u32_e32 v23, vcc, 0, v23, vcc
	global_load_dwordx4 v[38:41], v[22:23], off
	global_load_dwordx4 v[34:37], v[22:23], off offset:2048
	v_lshl_add_u64 v[22:23], s[4:5], 0, v[100:101]
	global_load_dwordx4 v[22:25], v[22:23], off
	s_and_b64 vcc, exec, s[50:51]
	s_cbranch_vccnz .LBB0_471
	v_mul_f32_e64 v42, v93, -v138
	s_nop 1
	v_add_f32_dpp v42, v42, v42 row_shr:1 row_mask:0xf bank_mask:0xf
	s_nop 1
	v_add_f32_dpp v42, v42, v42 row_shr:2 row_mask:0xf bank_mask:0xf
	s_nop 1
	v_add_f32_dpp v42, v42, v42 row_shr:4 row_mask:0xf bank_mask:0xf
	s_nop 1
	v_add_f32_dpp v42, v42, v42 row_shr:8 row_mask:0xf bank_mask:0xf
	s_nop 1
	v_add_f32_dpp v42, v42, v42 row_bcast:15 row_mask:0xa bank_mask:0xf
	s_nop 1
	v_add_f32_dpp v42, v42, v42 row_bcast:31 row_mask:0xc bank_mask:0xf
	s_nop 1
	v_lshl_or_b32 v43, s76, 8, v109
	v_add_u32_e32 v43, 0, v43
	v_add_u32_e32 v44, 0x17c00, v43
	ds_write_b32 v44, v42
	v_add_u32_e32 v42, 0x17e00, v43
	ds_write_b32 v42, v93
.LBB0_471:
	s_cmp_gt_u32 s63, 61
	s_cselect_b64 s[52:53], -1, 0
	s_or_b64 s[52:53], s[80:81], s[52:53]
	s_and_b64 vcc, exec, s[52:53]
	s_cbranch_vccnz .LBB0_473
	v_lshl_add_u64 v[42:43], s[4:5], 0, v[96:97]
	global_load_dword v93, v[42:43], off
; #define LAS __attribute__((address_space(3)))
; __device__ __forceinline__ unsigned cvt_pk_bf16(float lo, float hi) { unsigned r; asm volatile("v_cvt_pk_bf16_f32 %0, %1, %2" : "=v"(r) : "v"(lo), "v"(hi)); return r; }
; __device__ __forceinline__ void ssd_scan_mfma(const Ctx& c, bf16* X2, const float* DT, const float* a_log, const float* dskip, bool do_store) {
;     ...
;             {
;                 const float csl = CS[16 * lt + l15];
;                 bf16x8 Cf[4];
; #pragma unroll
;                 for (int ks = 0; ks < 4; ++ks) Cf[ks] = *(const LAS bf16x8*)(L + SS_C + (16 * lt + l15) * 272 + (32 * ks + 8 * lg) * 2);
;                 f32x4 GT[4];
; #pragma unroll
;                 for (int st = 0; st < 4; ++st) { GT[st] = (f32x4){0.f, 0.f, 0.f, 0.f};
;                     if (st <= lt) {
; #pragma unroll
;                         for (int ks = 0; ks < 4; ++ks) { const bf16x8 bf = *(const LAS bf16x8*)(L + SS_B + (16 * st + l15) * 272 + (32 * ks + 8 * lg) * 2); GT[st] = __builtin_amdgcn_mfma_f32_16x16x32_bf16(bf, Cf[ks], GT[st], 0, 0, 0); }
;                         const f32x4 css = *(const LAS f32x4*)(CS + 16 * st + 4 * lg);
; #pragma unroll
;                         for (int r = 0; r < 4; ++r) { const bool ok = (16 * st + 4 * lg + r) <= (16 * lt + l15); GT[st][r] = ok ? GT[st][r] * __expf(csl - css[r]) : 0.f; }
;                     } }
;                 bf16x8 Lf[2];
; #pragma unroll
;                 for (int k2 = 0; k2 < 2; ++k2) { v4u q; q.x = pg8::cvt_pk_bf16(GT[2 * k2][0], GT[2 * k2][1]); q.y = pg8::cvt_pk_bf16(GT[2 * k2][2], GT[2 * k2][3]); q.z = pg8::cvt_pk_bf16(GT[2 * k2 + 1][0], GT[2 * k2 + 1][1]); q.w = pg8::cvt_pk_bf16(GT[2 * k2 + 1][2], GT[2 * k2 + 1][3]);
;                     Lf[k2] = __builtin_bit_cast(bf16x8, q); }
;                 const float el = __expf(csl);
;                 const LAS unsigned char* xdb = L + SS_XD + (4 * lg + tq) * 144 + tp * 8;
; #pragma unroll
;                 for (int pp = 0; pp < 2; ++pp) { const int pt = 2 * ph + pp; f32x4 Y = (f32x4){0.f, 0.f, 0.f, 0.f}, Yo = (f32x4){0.f, 0.f, 0.f, 0.f};
; #pragma unroll
;                     for (int k2 = 0; k2 < 2; ++k2) if (2 * k2 <= lt) { const LAS unsigned char* xp = xdb + k2 * 32 * 144 + pt * 32;
;                         Y = __builtin_amdgcn_mfma_f32_16x16x32_bf16(cat8(tr16(xp), tr16(xp + 16 * 144)), Lf[k2], Y, 0, 0, 0); }
.LBB0_473:
	v_lshl_add_u32 v69, v74, 2, s65
	v_add_u32_e32 v139, v113, v114
	v_lshl_add_u32 v141, v116, 2, s65
	v_add_u32_e32 v140, s71, v117
	v_add_u32_e32 v68, s84, v117
	v_add_u32_e32 v54, s70, v119
	v_cndmask_b32_e64 v107, 0, 1, s[90:91]
	v_cmp_ne_u32_e64 s[54:55], 1, v107
	v_cndmask_b32_e64 v107, 0, 1, s[92:93]
	v_cmp_ne_u32_e64 s[52:53], 1, v107
	v_cndmask_b32_e64 v107, 0, 1, s[82:83]
	v_cmp_ne_u32_e64 s[56:57], 1, v107
	s_waitcnt lgkmcnt(0)
	s_barrier
	s_andn2_b64 vcc, exec, s[90:91]
	s_cbranch_vccnz .Lmy_scan_lt0
	s_andn2_b64 vcc, exec, s[92:93]
	s_cbranch_vccnz .Lmy_scan_lt1
	s_andn2_b64 vcc, exec, s[82:83]
	s_cbranch_vccnz .Lmy_scan_lt2
.Lmy_scan_lt3:
	ds_read_b32 v106, v69
	ds_read_b128 v[42:45], v139 offset:17408
	ds_read_b128 v[46:49], v139 offset:17472
	ds_read_b128 v[50:53], v139 offset:17536
	ds_read_b128 v[56:59], v139 offset:17600
	ds_read_b128 v[166:169], v133 offset:13056
	ds_read_b128 v[170:173], v133 offset:13120
	ds_read_b128 v[174:177], v133 offset:13184
	ds_read_b128 v[178:181], v133 offset:13248
	ds_read_b128 v[182:185], v141 offset:192
	s_mulk_i32 s96, 0x4400
	s_mulk_i32 s76, 0x4400
	s_add_u32 s10, s4, 0x23400000
	s_addc_u32 s11, s5, 0
	ds_read_b128 v[186:189], v133 offset:8704
	ds_read_b128 v[190:193], v133 offset:8768
	ds_read_b128 v[194:197], v133 offset:8832
	ds_read_b128 v[198:201], v133 offset:8896
	ds_read_b128 v[202:205], v141 offset:128
	v_add3_u32 v69, s96, v115, v120
	v_add3_u32 v107, s96, v115, v121
	v_add_u32_e32 v55, s76, v125
	s_waitcnt lgkmcnt(9)
	v_mfma_f32_16x16x32_bf16 v[166:169], v[166:169], v[42:45], 0
	s_waitcnt lgkmcnt(8)
	v_mfma_f32_16x16x32_bf16 v[166:169], v[170:173], v[46:49], v[166:169]
	s_waitcnt lgkmcnt(7)
	v_mfma_f32_16x16x32_bf16 v[166:169], v[174:177], v[50:53], v[166:169]
	s_waitcnt lgkmcnt(6)
	v_mfma_f32_16x16x32_bf16 v[166:169], v[178:181], v[56:59], v[166:169]
	ds_read_b128 v[206:209], v133 offset:4352
	ds_read_b128 v[210:213], v133 offset:4416
	ds_read_b128 v[214:217], v133 offset:4480
	ds_read_b128 v[218:221], v133 offset:4544
	ds_read_b128 v[222:225], v141 offset:64
	s_waitcnt lgkmcnt(9)
	v_mfma_f32_16x16x32_bf16 v[186:189], v[186:189], v[42:45], 0
	s_waitcnt lgkmcnt(8)
	v_mfma_f32_16x16x32_bf16 v[186:189], v[190:193], v[46:49], v[186:189]
	s_waitcnt lgkmcnt(7)
	v_mfma_f32_16x16x32_bf16 v[186:189], v[194:197], v[50:53], v[186:189]
	s_waitcnt lgkmcnt(6)
	v_mfma_f32_16x16x32_bf16 v[186:189], v[198:201], v[56:59], v[186:189]
	ds_read_b128 v[226:229], v133
	ds_read_b128 v[230:233], v133 offset:64
	ds_read_b128 v[234:237], v133 offset:128
	ds_read_b128 v[238:241], v133 offset:192
	ds_read_b128 v[242:245], v141
	v_sub_f32_e32 v182, v106, v182
	v_sub_f32_e32 v183, v106, v183
	v_sub_f32_e32 v184, v106, v184
	v_sub_f32_e32 v185, v106, v185
	v_mul_f32_e32 v182, 0x3fb8aa3b, v182
	v_mul_f32_e32 v183, 0x3fb8aa3b, v183
	v_mul_f32_e32 v184, 0x3fb8aa3b, v184
	v_mul_f32_e32 v185, 0x3fb8aa3b, v185
	v_exp_f32_e32 v182, v182
	v_exp_f32_e32 v183, v183
	v_exp_f32_e32 v184, v184
	v_exp_f32_e32 v185, v185
	v_mul_f32_e32 v166, v166, v182
	v_mul_f32_e32 v167, v167, v183
	v_mul_f32_e32 v168, v168, v184
	v_mul_f32_e32 v169, v169, v185
	v_cndmask_b32_e64 v166, v166, 0, s[42:43]
	v_cndmask_b32_e64 v167, v167, 0, s[44:45]
	v_cndmask_b32_e64 v168, v168, 0, s[46:47]
	v_cndmask_b32_e64 v169, v169, 0, s[48:49]
	s_waitcnt lgkmcnt(9)
	v_mfma_f32_16x16x32_bf16 v[206:209], v[206:209], v[42:45], 0
	s_waitcnt lgkmcnt(8)
	v_mfma_f32_16x16x32_bf16 v[206:209], v[210:213], v[46:49], v[206:209]
	s_waitcnt lgkmcnt(7)
	v_mfma_f32_16x16x32_bf16 v[206:209], v[214:217], v[50:53], v[206:209]
	s_waitcnt lgkmcnt(6)
	v_mfma_f32_16x16x32_bf16 v[206:209], v[218:221], v[56:59], v[206:209]
	ds_read_b64_tr_b16 v[60:61], v140 offset:44032
	ds_read_b64_tr_b16 v[62:63], v140 offset:46336
	ds_read_b64_tr_b16 v[64:65], v140 offset:48640
	ds_read_b64_tr_b16 v[66:67], v140 offset:50944
	v_sub_f32_e32 v202, v106, v202
	v_sub_f32_e32 v203, v106, v203
	v_sub_f32_e32 v204, v106, v204
	v_sub_f32_e32 v205, v106, v205
	v_mul_f32_e32 v202, 0x3fb8aa3b, v202
	v_mul_f32_e32 v203, 0x3fb8aa3b, v203
	v_mul_f32_e32 v204, 0x3fb8aa3b, v204
	v_mul_f32_e32 v205, 0x3fb8aa3b, v205
	v_exp_f32_e32 v202, v202
	v_exp_f32_e32 v203, v203
	v_exp_f32_e32 v204, v204
	v_exp_f32_e32 v205, v205
	v_mul_f32_e32 v186, v186, v202
	v_mul_f32_e32 v187, v187, v203
	v_mul_f32_e32 v188, v188, v204
	v_mul_f32_e32 v189, v189, v205
	v_cndmask_b32_e64 v186, v186, 0, s[34:35]
	v_cndmask_b32_e64 v187, v187, 0, s[36:37]
	v_cndmask_b32_e64 v188, v188, 0, s[38:39]
	v_cndmask_b32_e64 v189, v189, 0, s[40:41]
	s_waitcnt lgkmcnt(8)
	v_mfma_f32_16x16x32_bf16 v[226:229], v[226:229], v[42:45], 0
	s_waitcnt lgkmcnt(7)
	v_mfma_f32_16x16x32_bf16 v[226:229], v[230:233], v[46:49], v[226:229]
	s_waitcnt lgkmcnt(6)
	v_mfma_f32_16x16x32_bf16 v[226:229], v[234:237], v[50:53], v[226:229]
	s_waitcnt lgkmcnt(5)
	v_mfma_f32_16x16x32_bf16 v[226:229], v[238:241], v[56:59], v[226:229]
	ds_read_b64_tr_b16 v[142:143], v68 offset:44032
	ds_read_b64_tr_b16 v[144:145], v68 offset:46336
	ds_read_b64_tr_b16 v[146:147], v68 offset:48640
	ds_read_b64_tr_b16 v[148:149], v68 offset:50944
	v_sub_f32_e32 v222, v106, v222
	v_sub_f32_e32 v223, v106, v223
	v_sub_f32_e32 v224, v106, v224
	v_sub_f32_e32 v225, v106, v225
	v_mul_f32_e32 v222, 0x3fb8aa3b, v222
	v_mul_f32_e32 v223, 0x3fb8aa3b, v223
	v_mul_f32_e32 v224, 0x3fb8aa3b, v224
	v_mul_f32_e32 v225, 0x3fb8aa3b, v225
	v_exp_f32_e32 v222, v222
	v_exp_f32_e32 v223, v223
	v_exp_f32_e32 v224, v224
	v_exp_f32_e32 v225, v225
	v_mul_f32_e32 v206, v206, v222
	v_mul_f32_e32 v207, v207, v223
	v_mul_f32_e32 v208, v208, v224
	v_mul_f32_e32 v209, v209, v225
	v_cndmask_b32_e64 v206, v206, 0, s[24:25]
	v_cndmask_b32_e64 v207, v207, 0, s[26:27]
	v_cndmask_b32_e64 v208, v208, 0, s[28:29]
	v_cndmask_b32_e64 v209, v209, 0, s[30:31]
	ds_read_b128 v[150:153], v69 offset:62464
	ds_read_b128 v[154:157], v69 offset:62528
	ds_read_b128 v[158:161], v69 offset:62592
	ds_read_b128 v[246:249], v69 offset:62656
	ds_read_b64 v[162:163], v134 offset:34816
	s_waitcnt lgkmcnt(4)
; #define LAS __attribute__((address_space(3)))
; __device__ __forceinline__ void ssd_scan_mfma(const Ctx& c, bf16* X2, const float* DT, const float* a_log, const float* dskip, bool do_store) {
;     ...
; #pragma unroll
;                 for (int pp = 0; pp < 2; ++pp) { const int pt = 2 * ph + pp; f32x4 Y = (f32x4){0.f, 0.f, 0.f, 0.f}, Yo = (f32x4){0.f, 0.f, 0.f, 0.f};
; #pragma unroll
;                     for (int k2 = 0; k2 < 2; ++k2) if (2 * k2 <= lt) { const LAS unsigned char* xp = xdb + k2 * 32 * 144 + pt * 32;
;                         Y = __builtin_amdgcn_mfma_f32_16x16x32_bf16(cat8(tr16(xp), tr16(xp + 16 * 144)), Lf[k2], Y, 0, 0, 0); }
; #pragma unroll
;                     for (int ks = 0; ks < 4; ++ks) { const bf16x8 sb = *(const LAS bf16x8*)(SBr + (16 * pt + l15) * 272 + (32 * ks + 8 * lg) * 2); Yo = __builtin_amdgcn_mfma_f32_16x16x32_bf16(sb, Cf[ks], Yo, 0, 0, 0); }
;                     const v2u xr = *(const LAS v2u*)(L + SS_XR + (16 * lt + l15) * 144 + (16 * pt + 4 * lg) * 2);
;                     const float y0 = Y[0] + el * Yo[0] + Dh * bflo(xr.x), y1 = Y[1] + el * Yo[1] + Dh * bfhi(xr.x), y2 = Y[2] + el * Yo[2] + Dh * bflo(xr.y), y3 = Y[3] + el * Yo[3] + Dh * bfhi(xr.y);
;                     v2u o; o.x = pk2(y0, y1); o.y = pk2(y2, y3);
;                     if (do_store) *(v2u*)(X2 + ((size_t)b * SEQ + t0 + 16 * lt + l15) * 6144 + h * 64 + 16 * pt + 4 * lg) = o; }
;                 const float e63 = __expf(CS[63]); const int pts = w >> 1;
;                 const LAS unsigned char* bb = L + SS_B + (8 * lg + tq) * 272 + tp * 8; const LAS unsigned char* xwb = L + SS_XW + (8 * lg + tq) * 144 + tp * 8 + pts * 32;
;                 bf16x8 Xf[2];
; #pragma unroll
;                 for (int ks = 0; ks < 2; ++ks) Xf[ks] = cat8(tr16(xwb + ks * 32 * 144), tr16(xwb + ks * 32 * 144 + 4 * 144));
; #pragma unroll
;                 for (int i = 0; i < 4; ++i) { const int nt = 4 * (w & 1) + i; ST[i] *= e63;
; #pragma unroll
;                     for (int ks = 0; ks < 2; ++ks) { const LAS unsigned char* bp = bb + ks * 32 * 272 + nt * 32;
;                         ST[i] = __builtin_amdgcn_mfma_f32_16x16x32_bf16(cat8(tr16(bp), tr16(bp + 4 * 272)), Xf[ks], ST[i], 0, 0, 0); }
;                     v2u q; q.x = pk2(ST[i][0], ST[i][1]); q.y = pk2(ST[i][2], ST[i][3]);
;                     *(LAS v2u*)(SBw + (16 * pts + l15) * 272 + (16 * nt + 4 * lg) * 2) = q; }
	v_mfma_f32_16x16x32_bf16 v[150:153], v[150:153], v[42:45], 0
	s_waitcnt lgkmcnt(3)
	v_mfma_f32_16x16x32_bf16 v[150:153], v[154:157], v[46:49], v[150:153]
	s_waitcnt lgkmcnt(2)
	v_mfma_f32_16x16x32_bf16 v[150:153], v[158:161], v[50:53], v[150:153]
	s_waitcnt lgkmcnt(1)
	v_mfma_f32_16x16x32_bf16 v[150:153], v[246:249], v[56:59], v[150:153]
	v_sub_f32_e32 v242, v106, v242
	v_sub_f32_e32 v243, v106, v243
	v_sub_f32_e32 v244, v106, v244
	v_sub_f32_e32 v245, v106, v245
	v_mul_f32_e32 v242, 0x3fb8aa3b, v242
	v_mul_f32_e32 v243, 0x3fb8aa3b, v243
	v_mul_f32_e32 v244, 0x3fb8aa3b, v244
	v_mul_f32_e32 v245, 0x3fb8aa3b, v245
	v_exp_f32_e32 v242, v242
	v_exp_f32_e32 v243, v243
	v_exp_f32_e32 v244, v244
	v_exp_f32_e32 v245, v245
	v_mul_f32_e32 v226, v226, v242
	v_mul_f32_e32 v227, v227, v243
	v_mul_f32_e32 v228, v228, v244
	v_mul_f32_e32 v229, v229, v245
	v_cndmask_b32_e64 v226, v226, 0, s[16:17]
	v_cndmask_b32_e64 v227, 0, v227, s[18:19]
	v_cndmask_b32_e64 v228, v228, 0, s[20:21]
	v_cndmask_b32_e64 v229, v229, 0, s[22:23]
	v_mul_f32_e32 v106, 0x3fb8aa3b, v106
	v_exp_f32_e32 v106, v106
	v_cvt_pk_bf16_f32 v226, v226, v227
	v_cvt_pk_bf16_f32 v227, v228, v229
	v_cvt_pk_bf16_f32 v228, v206, v207
	v_cvt_pk_bf16_f32 v229, v208, v209
	v_cvt_pk_bf16_f32 v186, v186, v187
	v_cvt_pk_bf16_f32 v187, v188, v189
	v_cvt_pk_bf16_f32 v188, v166, v167
	v_cvt_pk_bf16_f32 v189, v168, v169
	v_mov_b32_e32 v168, s65
	ds_read_b128 v[170:173], v107 offset:62464
	ds_read_b128 v[174:177], v107 offset:62528
	ds_read_b128 v[178:181], v107 offset:62592
	ds_read_b128 v[182:185], v107 offset:62656
	ds_read_b64 v[166:167], v136 offset:34816
	ds_read_b32 v168, v168 offset:252
	v_lshl_add_u64 v[238:239], s[10:11], 0, v[98:99]
	v_mfma_f32_16x16x32_bf16 v[60:63], v[60:63], v[226:229], 0
	v_mfma_f32_16x16x32_bf16 v[60:63], v[64:67], v[186:189], v[60:63]
	v_mfma_f32_16x16x32_bf16 v[142:145], v[142:145], v[226:229], 0
	v_mfma_f32_16x16x32_bf16 v[142:145], v[146:149], v[186:189], v[142:145]
	s_waitcnt lgkmcnt(5)
	v_mfma_f32_16x16x32_bf16 v[170:173], v[170:173], v[42:45], 0
	s_waitcnt lgkmcnt(4)
	v_mfma_f32_16x16x32_bf16 v[170:173], v[174:177], v[46:49], v[170:173]
	s_waitcnt lgkmcnt(3)
	v_mfma_f32_16x16x32_bf16 v[170:173], v[178:181], v[50:53], v[170:173]
	s_waitcnt lgkmcnt(2)
	v_mfma_f32_16x16x32_bf16 v[170:173], v[182:185], v[56:59], v[170:173]
	ds_read_b64_tr_b16 v[190:191], v137 offset:53248
	ds_read_b64_tr_b16 v[192:193], v137 offset:53824
	ds_read_b64_tr_b16 v[194:195], v137 offset:57856
	ds_read_b64_tr_b16 v[196:197], v137 offset:58432
	ds_read_b64_tr_b16 v[198:199], v54
	ds_read_b64_tr_b16 v[200:201], v54 offset:1088
	ds_read_b64_tr_b16 v[202:203], v54 offset:8704
	ds_read_b64_tr_b16 v[204:205], v54 offset:9792
	s_waitcnt lgkmcnt(8)
	v_mul_f32_e32 v168, 0x3fb8aa3b, v168
	v_exp_f32_e32 v168, v168
	v_fma_f32 v60, v106, v150, v60
	v_fma_f32 v61, v106, v151, v61
	v_fma_f32 v62, v106, v152, v62
	v_fma_f32 v63, v106, v153, v63
	v_lshlrev_b32_e32 v150, 16, v162
	v_and_b32_e32 v151, 0xffff0000, v162
	v_lshlrev_b32_e32 v152, 16, v163
	v_and_b32_e32 v153, 0xffff0000, v163
	v_fma_f32 v60, v94, v150, v60
	v_fma_f32 v61, v94, v151, v61
	v_fma_f32 v62, v95, v152, v62
	v_fma_f32 v63, v95, v153, v63
	v_cvt_pk_bf16_f32 v162, v60, v61
	v_cvt_pk_bf16_f32 v163, v62, v63
	global_store_dwordx2 v[238:239], v[162:163], off
	v_pk_mul_f32 v[18:19], v[18:19], v[168:169] op_sel_hi:[1,0]
	v_pk_mul_f32 v[20:21], v[20:21], v[168:169] op_sel_hi:[1,0]
	v_pk_mul_f32 v[14:15], v[14:15], v[168:169] op_sel_hi:[1,0]
	v_pk_mul_f32 v[16:17], v[16:17], v[168:169] op_sel_hi:[1,0]
	v_pk_mul_f32 v[10:11], v[10:11], v[168:169] op_sel_hi:[1,0]
	v_pk_mul_f32 v[12:13], v[12:13], v[168:169] op_sel_hi:[1,0]
	v_pk_mul_f32 v[6:7], v[6:7], v[168:169] op_sel_hi:[1,0]
	v_pk_mul_f32 v[8:9], v[8:9], v[168:169] op_sel_hi:[1,0]
	s_waitcnt lgkmcnt(2)
	v_mfma_f32_16x16x32_bf16 v[18:21], v[198:201], v[190:193], v[18:21]
	s_waitcnt lgkmcnt(0)
	v_mfma_f32_16x16x32_bf16 v[18:21], v[202:205], v[194:197], v[18:21]
	ds_read_b64_tr_b16 v[210:211], v54 offset:32
	ds_read_b64_tr_b16 v[212:213], v54 offset:1120
	ds_read_b64_tr_b16 v[214:215], v54 offset:8736
	ds_read_b64_tr_b16 v[216:217], v54 offset:9824
	v_fma_f32 v142, v106, v170, v142
	v_fma_f32 v143, v106, v171, v143
	v_fma_f32 v144, v106, v172, v144
	v_fma_f32 v145, v106, v173, v145
	v_lshlrev_b32_e32 v170, 16, v166
	v_and_b32_e32 v171, 0xffff0000, v166
	v_lshlrev_b32_e32 v172, 16, v167
	v_and_b32_e32 v173, 0xffff0000, v167
	v_fma_f32 v142, v94, v170, v142
	v_fma_f32 v143, v94, v171, v143
	v_fma_f32 v144, v95, v172, v144
	v_fma_f32 v145, v95, v173, v145
	v_cvt_pk_bf16_f32 v166, v142, v143
	v_cvt_pk_bf16_f32 v167, v144, v145
	global_store_dwordx2 v[238:239], v[166:167], off offset:32
	s_waitcnt lgkmcnt(2)
	v_mfma_f32_16x16x32_bf16 v[14:17], v[210:213], v[190:193], v[14:17]
	s_waitcnt lgkmcnt(0)
	v_mfma_f32_16x16x32_bf16 v[14:17], v[214:217], v[194:197], v[14:17]
	ds_read_b64_tr_b16 v[218:219], v54 offset:64
	ds_read_b64_tr_b16 v[220:221], v54 offset:1152
	ds_read_b64_tr_b16 v[222:223], v54 offset:8768
	ds_read_b64_tr_b16 v[224:225], v54 offset:9856
	v_cvt_pk_bf16_f32 v240, v18, v19
	v_cvt_pk_bf16_f32 v241, v20, v21
	ds_write_b64 v55, v[240:241] offset:62464
	s_waitcnt lgkmcnt(3)
	v_mfma_f32_16x16x32_bf16 v[10:13], v[218:221], v[190:193], v[10:13]
	s_waitcnt lgkmcnt(1)
	v_mfma_f32_16x16x32_bf16 v[10:13], v[222:225], v[194:197], v[10:13]
	ds_read_b64_tr_b16 v[230:231], v54 offset:96
	ds_read_b64_tr_b16 v[232:233], v54 offset:1184
	ds_read_b64_tr_b16 v[234:235], v54 offset:8800
	ds_read_b64_tr_b16 v[236:237], v54 offset:9888
	v_cvt_pk_bf16_f32 v242, v14, v15
	v_cvt_pk_bf16_f32 v243, v16, v17
	ds_write_b64 v55, v[242:243] offset:62496
	s_waitcnt lgkmcnt(3)
	v_mfma_f32_16x16x32_bf16 v[6:9], v[230:233], v[190:193], v[6:9]
	s_waitcnt lgkmcnt(1)
	v_mfma_f32_16x16x32_bf16 v[6:9], v[234:237], v[194:197], v[6:9]
	s_mov_b64 s[96:97], 0x4000
	s_add_i32 s63, s63, 1
	v_lshl_add_u64 v[96:97], v[96:97], 0, s[96:97]
	v_lshl_add_u64 v[98:99], v[98:99], 0, s[58:59]
	v_lshl_add_u64 v[100:101], v[100:101], 0, s[58:59]
	v_lshl_add_u64 v[102:103], v[102:103], 0, s[58:59]
	v_lshl_add_u64 v[104:105], v[104:105], 0, s[58:59]
	v_cvt_pk_bf16_f32 v240, v10, v11
	v_cvt_pk_bf16_f32 v241, v12, v13
	ds_write_b64 v55, v[240:241] offset:62528
	s_cmp_eq_u32 s63, 63
	v_cvt_pk_bf16_f32 v242, v6, v7
	v_cvt_pk_bf16_f32 v243, v8, v9
	ds_write_b64 v55, v[242:243] offset:62560
	s_cbranch_scc1 .LBB0_483
	s_branch .LBB0_469
; __device__ __forceinline__ void ssd_scan_mfma(const Ctx& c, bf16* X2, const float* DT, const float* a_log, const float* dskip, bool do_store) {
;     ...
;             {
;                 const float csl = CS[16 * lt + l15];
;                 bf16x8 Cf[4];
; #pragma unroll
;                 for (int ks = 0; ks < 4; ++ks) Cf[ks] = *(const LAS bf16x8*)(L + SS_C + (16 * lt + l15) * 272 + (32 * ks + 8 * lg) * 2);
;                 f32x4 GT[4];
; #pragma unroll
;                 for (int st = 0; st < 4; ++st) { GT[st] = (f32x4){0.f, 0.f, 0.f, 0.f};
;                     if (st <= lt) {
; #pragma unroll
;                         for (int ks = 0; ks < 4; ++ks) { const bf16x8 bf = *(const LAS bf16x8*)(L + SS_B + (16 * st + l15) * 272 + (32 * ks + 8 * lg) * 2); GT[st] = __builtin_amdgcn_mfma_f32_16x16x32_bf16(bf, Cf[ks], GT[st], 0, 0, 0); }
;                         const f32x4 css = *(const LAS f32x4*)(CS + 16 * st + 4 * lg);
; #pragma unroll
;                         for (int r = 0; r < 4; ++r) { const bool ok = (16 * st + 4 * lg + r) <= (16 * lt + l15); GT[st][r] = ok ? GT[st][r] * __expf(csl - css[r]) : 0.f; }
;                     } }
;                 bf16x8 Lf[2];
; #pragma unroll
;                 for (int k2 = 0; k2 < 2; ++k2) { v4u q; q.x = pg8::cvt_pk_bf16(GT[2 * k2][0], GT[2 * k2][1]); q.y = pg8::cvt_pk_bf16(GT[2 * k2][2], GT[2 * k2][3]); q.z = pg8::cvt_pk_bf16(GT[2 * k2 + 1][0], GT[2 * k2 + 1][1]); q.w = pg8::cvt_pk_bf16(GT[2 * k2 + 1][2], GT[2 * k2 + 1][3]);
;                     Lf[k2] = __builtin_bit_cast(bf16x8, q); }
;                 const float el = __expf(csl);
;                 const LAS unsigned char* xdb = L + SS_XD + (4 * lg + tq) * 144 + tp * 8;
; #pragma unroll
;                 for (int pp = 0; pp < 2; ++pp) { const int pt = 2 * ph + pp; f32x4 Y = (f32x4){0.f, 0.f, 0.f, 0.f}, Yo = (f32x4){0.f, 0.f, 0.f, 0.f};
; #pragma unroll
;                     for (int k2 = 0; k2 < 2; ++k2) if (2 * k2 <= lt) { const LAS unsigned char* xp = xdb + k2 * 32 * 144 + pt * 32;
;                         Y = __builtin_amdgcn_mfma_f32_16x16x32_bf16(cat8(tr16(xp), tr16(xp + 16 * 144)), Lf[k2], Y, 0, 0, 0); }
; #pragma unroll
;                     for (int ks = 0; ks < 4; ++ks) { const bf16x8 sb = *(const LAS bf16x8*)(SBr + (16 * pt + l15) * 272 + (32 * ks + 8 * lg) * 2); Yo = __builtin_amdgcn_mfma_f32_16x16x32_bf16(sb, Cf[ks], Yo, 0, 0, 0); }
.Lmy_scan_lt2:
	ds_read_b32 v106, v69
	ds_read_b128 v[42:45], v139 offset:17408
	ds_read_b128 v[46:49], v139 offset:17472
	ds_read_b128 v[50:53], v139 offset:17536
	ds_read_b128 v[56:59], v139 offset:17600
	ds_read_b128 v[186:189], v133 offset:8704
	ds_read_b128 v[190:193], v133 offset:8768
	ds_read_b128 v[194:197], v133 offset:8832
	ds_read_b128 v[198:201], v133 offset:8896
	ds_read_b128 v[202:205], v141 offset:128
	s_mulk_i32 s96, 0x4400
	s_mulk_i32 s76, 0x4400
	s_add_u32 s10, s4, 0x23400000
	s_addc_u32 s11, s5, 0
	ds_read_b128 v[206:209], v133 offset:4352
	ds_read_b128 v[210:213], v133 offset:4416
	ds_read_b128 v[214:217], v133 offset:4480
	ds_read_b128 v[218:221], v133 offset:4544
	ds_read_b128 v[222:225], v141 offset:64
	v_add3_u32 v69, s96, v115, v120
	v_add3_u32 v107, s96, v115, v121
	v_add_u32_e32 v55, s76, v125
	s_waitcnt lgkmcnt(9)
	v_mfma_f32_16x16x32_bf16 v[186:189], v[186:189], v[42:45], 0
	s_waitcnt lgkmcnt(8)
	v_mfma_f32_16x16x32_bf16 v[186:189], v[190:193], v[46:49], v[186:189]
	s_waitcnt lgkmcnt(7)
	v_mfma_f32_16x16x32_bf16 v[186:189], v[194:197], v[50:53], v[186:189]
	s_waitcnt lgkmcnt(6)
	v_mfma_f32_16x16x32_bf16 v[186:189], v[198:201], v[56:59], v[186:189]
	ds_read_b128 v[226:229], v133
	ds_read_b128 v[230:233], v133 offset:64
	ds_read_b128 v[234:237], v133 offset:128
	ds_read_b128 v[238:241], v133 offset:192
	ds_read_b128 v[242:245], v141
	s_waitcnt lgkmcnt(9)
	v_mfma_f32_16x16x32_bf16 v[206:209], v[206:209], v[42:45], 0
	s_waitcnt lgkmcnt(8)
	v_mfma_f32_16x16x32_bf16 v[206:209], v[210:213], v[46:49], v[206:209]
	s_waitcnt lgkmcnt(7)
	v_mfma_f32_16x16x32_bf16 v[206:209], v[214:217], v[50:53], v[206:209]
	s_waitcnt lgkmcnt(6)
	v_mfma_f32_16x16x32_bf16 v[206:209], v[218:221], v[56:59], v[206:209]
	ds_read_b64_tr_b16 v[60:61], v140 offset:44032
	ds_read_b64_tr_b16 v[62:63], v140 offset:46336
	ds_read_b64_tr_b16 v[64:65], v140 offset:48640
	ds_read_b64_tr_b16 v[66:67], v140 offset:50944
	v_sub_f32_e32 v202, v106, v202
	v_sub_f32_e32 v203, v106, v203
	v_sub_f32_e32 v204, v106, v204
	v_sub_f32_e32 v205, v106, v205
	v_mul_f32_e32 v202, 0x3fb8aa3b, v202
	v_mul_f32_e32 v203, 0x3fb8aa3b, v203
	v_mul_f32_e32 v204, 0x3fb8aa3b, v204
	v_mul_f32_e32 v205, 0x3fb8aa3b, v205
	v_exp_f32_e32 v202, v202
	v_exp_f32_e32 v203, v203
	v_exp_f32_e32 v204, v204
	v_exp_f32_e32 v205, v205
	v_mul_f32_e32 v186, v186, v202
	v_mul_f32_e32 v187, v187, v203
	v_mul_f32_e32 v188, v188, v204
	v_mul_f32_e32 v189, v189, v205
	v_cndmask_b32_e64 v186, v186, 0, s[34:35]
	v_cndmask_b32_e64 v187, v187, 0, s[36:37]
	v_cndmask_b32_e64 v188, v188, 0, s[38:39]
	v_cndmask_b32_e64 v189, v189, 0, s[40:41]
	s_waitcnt lgkmcnt(8)
	v_mfma_f32_16x16x32_bf16 v[226:229], v[226:229], v[42:45], 0
	s_waitcnt lgkmcnt(7)
	v_mfma_f32_16x16x32_bf16 v[226:229], v[230:233], v[46:49], v[226:229]
	s_waitcnt lgkmcnt(6)
	v_mfma_f32_16x16x32_bf16 v[226:229], v[234:237], v[50:53], v[226:229]
	s_waitcnt lgkmcnt(5)
	v_mfma_f32_16x16x32_bf16 v[226:229], v[238:241], v[56:59], v[226:229]
	ds_read_b64_tr_b16 v[142:143], v68 offset:44032
	ds_read_b64_tr_b16 v[144:145], v68 offset:46336
	ds_read_b64_tr_b16 v[146:147], v68 offset:48640
	ds_read_b64_tr_b16 v[148:149], v68 offset:50944
	v_sub_f32_e32 v222, v106, v222
	v_sub_f32_e32 v223, v106, v223
	v_sub_f32_e32 v224, v106, v224
	v_sub_f32_e32 v225, v106, v225
	v_mul_f32_e32 v222, 0x3fb8aa3b, v222
	v_mul_f32_e32 v223, 0x3fb8aa3b, v223
	v_mul_f32_e32 v224, 0x3fb8aa3b, v224
	v_mul_f32_e32 v225, 0x3fb8aa3b, v225
	v_exp_f32_e32 v222, v222
	v_exp_f32_e32 v223, v223
	v_exp_f32_e32 v224, v224
	v_exp_f32_e32 v225, v225
	v_mul_f32_e32 v206, v206, v222
	v_mul_f32_e32 v207, v207, v223
	v_mul_f32_e32 v208, v208, v224
	v_mul_f32_e32 v209, v209, v225
	v_cndmask_b32_e64 v206, v206, 0, s[24:25]
	v_cndmask_b32_e64 v207, v207, 0, s[26:27]
	v_cndmask_b32_e64 v208, v208, 0, s[28:29]
	v_cndmask_b32_e64 v209, v209, 0, s[30:31]
	ds_read_b128 v[150:153], v69 offset:62464
	ds_read_b128 v[154:157], v69 offset:62528
	ds_read_b128 v[158:161], v69 offset:62592
	ds_read_b128 v[246:249], v69 offset:62656
	ds_read_b64 v[162:163], v134 offset:34816
	s_waitcnt lgkmcnt(4)
	v_mfma_f32_16x16x32_bf16 v[150:153], v[150:153], v[42:45], 0
	s_waitcnt lgkmcnt(3)
	v_mfma_f32_16x16x32_bf16 v[150:153], v[154:157], v[46:49], v[150:153]
	s_waitcnt lgkmcnt(2)
	v_mfma_f32_16x16x32_bf16 v[150:153], v[158:161], v[50:53], v[150:153]
	s_waitcnt lgkmcnt(1)
	v_mfma_f32_16x16x32_bf16 v[150:153], v[246:249], v[56:59], v[150:153]
	v_sub_f32_e32 v242, v106, v242
	v_sub_f32_e32 v243, v106, v243
	v_sub_f32_e32 v244, v106, v244
	v_sub_f32_e32 v245, v106, v245
	v_mul_f32_e32 v242, 0x3fb8aa3b, v242
	v_mul_f32_e32 v243, 0x3fb8aa3b, v243
	v_mul_f32_e32 v244, 0x3fb8aa3b, v244
	v_mul_f32_e32 v245, 0x3fb8aa3b, v245
	v_exp_f32_e32 v242, v242
	v_exp_f32_e32 v243, v243
	v_exp_f32_e32 v244, v244
	v_exp_f32_e32 v245, v245
	v_mul_f32_e32 v226, v226, v242
	v_mul_f32_e32 v227, v227, v243
	v_mul_f32_e32 v228, v228, v244
	v_mul_f32_e32 v229, v229, v245
	v_cndmask_b32_e64 v226, v226, 0, s[16:17]
	v_cndmask_b32_e64 v227, 0, v227, s[18:19]
	v_cndmask_b32_e64 v228, v228, 0, s[20:21]
	v_cndmask_b32_e64 v229, v229, 0, s[22:23]
	v_mul_f32_e32 v106, 0x3fb8aa3b, v106
	v_exp_f32_e32 v106, v106
	v_cvt_pk_bf16_f32 v226, v226, v227
	v_cvt_pk_bf16_f32 v227, v228, v229
	v_cvt_pk_bf16_f32 v228, v206, v207
	v_cvt_pk_bf16_f32 v229, v208, v209
	v_cvt_pk_bf16_f32 v186, v186, v187
	v_cvt_pk_bf16_f32 v187, v188, v189
	v_mov_b32_e32 v188, 0
	v_mov_b32_e32 v189, 0
	v_mov_b32_e32 v168, s65
	ds_read_b128 v[170:173], v107 offset:62464
	ds_read_b128 v[174:177], v107 offset:62528
	ds_read_b128 v[178:181], v107 offset:62592
	ds_read_b128 v[182:185], v107 offset:62656
	ds_read_b64 v[166:167], v136 offset:34816
	ds_read_b32 v168, v168 offset:252
	v_lshl_add_u64 v[238:239], s[10:11], 0, v[98:99]
	v_mfma_f32_16x16x32_bf16 v[60:63], v[60:63], v[226:229], 0
	v_mfma_f32_16x16x32_bf16 v[60:63], v[64:67], v[186:189], v[60:63]
	v_mfma_f32_16x16x32_bf16 v[142:145], v[142:145], v[226:229], 0
	v_mfma_f32_16x16x32_bf16 v[142:145], v[146:149], v[186:189], v[142:145]
	s_waitcnt lgkmcnt(5)
; #define LAS __attribute__((address_space(3)))
; __device__ __forceinline__ unsigned pk2(float lo, float hi) { return f2bf(lo) | (f2bf(hi) << 16); }
; __device__ __forceinline__ s16x4 tr16(const LAS unsigned char* p) { return __builtin_amdgcn_ds_read_tr16_b64_v4i16((LAS s16x4*)p); }
; __device__ __forceinline__ void ssd_scan_mfma(const Ctx& c, bf16* X2, const float* DT, const float* a_log, const float* dskip, bool do_store) {
;     ...
;                     for (int ks = 0; ks < 4; ++ks) { const bf16x8 sb = *(const LAS bf16x8*)(SBr + (16 * pt + l15) * 272 + (32 * ks + 8 * lg) * 2); Yo = __builtin_amdgcn_mfma_f32_16x16x32_bf16(sb, Cf[ks], Yo, 0, 0, 0); }
;                     const v2u xr = *(const LAS v2u*)(L + SS_XR + (16 * lt + l15) * 144 + (16 * pt + 4 * lg) * 2);
;                     const float y0 = Y[0] + el * Yo[0] + Dh * bflo(xr.x), y1 = Y[1] + el * Yo[1] + Dh * bfhi(xr.x), y2 = Y[2] + el * Yo[2] + Dh * bflo(xr.y), y3 = Y[3] + el * Yo[3] + Dh * bfhi(xr.y);
;                     v2u o; o.x = pk2(y0, y1); o.y = pk2(y2, y3);
;                     if (do_store) *(v2u*)(X2 + ((size_t)b * SEQ + t0 + 16 * lt + l15) * 6144 + h * 64 + 16 * pt + 4 * lg) = o; }
;                 const float e63 = __expf(CS[63]); const int pts = w >> 1;
;                 const LAS unsigned char* bb = L + SS_B + (8 * lg + tq) * 272 + tp * 8; const LAS unsigned char* xwb = L + SS_XW + (8 * lg + tq) * 144 + tp * 8 + pts * 32;
;                 bf16x8 Xf[2];
; #pragma unroll
;                 for (int ks = 0; ks < 2; ++ks) Xf[ks] = cat8(tr16(xwb + ks * 32 * 144), tr16(xwb + ks * 32 * 144 + 4 * 144));
; #pragma unroll
;                 for (int i = 0; i < 4; ++i) { const int nt = 4 * (w & 1) + i; ST[i] *= e63;
; #pragma unroll
;                     for (int ks = 0; ks < 2; ++ks) { const LAS unsigned char* bp = bb + ks * 32 * 272 + nt * 32;
;                         ST[i] = __builtin_amdgcn_mfma_f32_16x16x32_bf16(cat8(tr16(bp), tr16(bp + 4 * 272)), Xf[ks], ST[i], 0, 0, 0); }
;                     v2u q; q.x = pk2(ST[i][0], ST[i][1]); q.y = pk2(ST[i][2], ST[i][3]);
;                     *(LAS v2u*)(SBw + (16 * pts + l15) * 272 + (16 * nt + 4 * lg) * 2) = q; }
	v_mfma_f32_16x16x32_bf16 v[170:173], v[170:173], v[42:45], 0
	s_waitcnt lgkmcnt(4)
	v_mfma_f32_16x16x32_bf16 v[170:173], v[174:177], v[46:49], v[170:173]
	s_waitcnt lgkmcnt(3)
	v_mfma_f32_16x16x32_bf16 v[170:173], v[178:181], v[50:53], v[170:173]
	s_waitcnt lgkmcnt(2)
	v_mfma_f32_16x16x32_bf16 v[170:173], v[182:185], v[56:59], v[170:173]
	ds_read_b64_tr_b16 v[190:191], v137 offset:53248
	ds_read_b64_tr_b16 v[192:193], v137 offset:53824
	ds_read_b64_tr_b16 v[194:195], v137 offset:57856
	ds_read_b64_tr_b16 v[196:197], v137 offset:58432
	ds_read_b64_tr_b16 v[198:199], v54
	ds_read_b64_tr_b16 v[200:201], v54 offset:1088
	ds_read_b64_tr_b16 v[202:203], v54 offset:8704
	ds_read_b64_tr_b16 v[204:205], v54 offset:9792
	s_waitcnt lgkmcnt(8)
	v_mul_f32_e32 v168, 0x3fb8aa3b, v168
	v_exp_f32_e32 v168, v168
	v_fma_f32 v60, v106, v150, v60
	v_fma_f32 v61, v106, v151, v61
	v_fma_f32 v62, v106, v152, v62
	v_fma_f32 v63, v106, v153, v63
	v_lshlrev_b32_e32 v150, 16, v162
	v_and_b32_e32 v151, 0xffff0000, v162
	v_lshlrev_b32_e32 v152, 16, v163
	v_and_b32_e32 v153, 0xffff0000, v163
	v_fma_f32 v60, v94, v150, v60
	v_fma_f32 v61, v94, v151, v61
	v_fma_f32 v62, v95, v152, v62
	v_fma_f32 v63, v95, v153, v63
	v_cvt_pk_bf16_f32 v162, v60, v61
	v_cvt_pk_bf16_f32 v163, v62, v63
	global_store_dwordx2 v[238:239], v[162:163], off
	v_pk_mul_f32 v[18:19], v[18:19], v[168:169] op_sel_hi:[1,0]
	v_pk_mul_f32 v[20:21], v[20:21], v[168:169] op_sel_hi:[1,0]
	v_pk_mul_f32 v[14:15], v[14:15], v[168:169] op_sel_hi:[1,0]
	v_pk_mul_f32 v[16:17], v[16:17], v[168:169] op_sel_hi:[1,0]
	v_pk_mul_f32 v[10:11], v[10:11], v[168:169] op_sel_hi:[1,0]
	v_pk_mul_f32 v[12:13], v[12:13], v[168:169] op_sel_hi:[1,0]
	v_pk_mul_f32 v[6:7], v[6:7], v[168:169] op_sel_hi:[1,0]
	v_pk_mul_f32 v[8:9], v[8:9], v[168:169] op_sel_hi:[1,0]
	s_waitcnt lgkmcnt(2)
	v_mfma_f32_16x16x32_bf16 v[18:21], v[198:201], v[190:193], v[18:21]
	s_waitcnt lgkmcnt(0)
	v_mfma_f32_16x16x32_bf16 v[18:21], v[202:205], v[194:197], v[18:21]
	ds_read_b64_tr_b16 v[210:211], v54 offset:32
	ds_read_b64_tr_b16 v[212:213], v54 offset:1120
	ds_read_b64_tr_b16 v[214:215], v54 offset:8736
	ds_read_b64_tr_b16 v[216:217], v54 offset:9824
	v_fma_f32 v142, v106, v170, v142
	v_fma_f32 v143, v106, v171, v143
	v_fma_f32 v144, v106, v172, v144
	v_fma_f32 v145, v106, v173, v145
	v_lshlrev_b32_e32 v170, 16, v166
	v_and_b32_e32 v171, 0xffff0000, v166
	v_lshlrev_b32_e32 v172, 16, v167
	v_and_b32_e32 v173, 0xffff0000, v167
	v_fma_f32 v142, v94, v170, v142
	v_fma_f32 v143, v94, v171, v143
	v_fma_f32 v144, v95, v172, v144
	v_fma_f32 v145, v95, v173, v145
	v_cvt_pk_bf16_f32 v166, v142, v143
	v_cvt_pk_bf16_f32 v167, v144, v145
	global_store_dwordx2 v[238:239], v[166:167], off offset:32
	s_waitcnt lgkmcnt(2)
	v_mfma_f32_16x16x32_bf16 v[14:17], v[210:213], v[190:193], v[14:17]
	s_waitcnt lgkmcnt(0)
	v_mfma_f32_16x16x32_bf16 v[14:17], v[214:217], v[194:197], v[14:17]
	ds_read_b64_tr_b16 v[218:219], v54 offset:64
	ds_read_b64_tr_b16 v[220:221], v54 offset:1152
	ds_read_b64_tr_b16 v[222:223], v54 offset:8768
	ds_read_b64_tr_b16 v[224:225], v54 offset:9856
	v_cvt_pk_bf16_f32 v240, v18, v19
	v_cvt_pk_bf16_f32 v241, v20, v21
	ds_write_b64 v55, v[240:241] offset:62464
	s_waitcnt lgkmcnt(3)
	v_mfma_f32_16x16x32_bf16 v[10:13], v[218:221], v[190:193], v[10:13]
	s_waitcnt lgkmcnt(1)
	v_mfma_f32_16x16x32_bf16 v[10:13], v[222:225], v[194:197], v[10:13]
	ds_read_b64_tr_b16 v[230:231], v54 offset:96
	ds_read_b64_tr_b16 v[232:233], v54 offset:1184
	ds_read_b64_tr_b16 v[234:235], v54 offset:8800
	ds_read_b64_tr_b16 v[236:237], v54 offset:9888
	v_cvt_pk_bf16_f32 v242, v14, v15
	v_cvt_pk_bf16_f32 v243, v16, v17
	ds_write_b64 v55, v[242:243] offset:62496
	s_waitcnt lgkmcnt(3)
	v_mfma_f32_16x16x32_bf16 v[6:9], v[230:233], v[190:193], v[6:9]
	s_waitcnt lgkmcnt(1)
	v_mfma_f32_16x16x32_bf16 v[6:9], v[234:237], v[194:197], v[6:9]
	s_mov_b64 s[96:97], 0x4000
	s_add_i32 s63, s63, 1
	v_lshl_add_u64 v[96:97], v[96:97], 0, s[96:97]
	v_lshl_add_u64 v[98:99], v[98:99], 0, s[58:59]
	v_lshl_add_u64 v[100:101], v[100:101], 0, s[58:59]
	v_lshl_add_u64 v[102:103], v[102:103], 0, s[58:59]
	v_lshl_add_u64 v[104:105], v[104:105], 0, s[58:59]
	v_cvt_pk_bf16_f32 v240, v10, v11
	v_cvt_pk_bf16_f32 v241, v12, v13
	ds_write_b64 v55, v[240:241] offset:62528
	s_cmp_eq_u32 s63, 63
	v_cvt_pk_bf16_f32 v242, v6, v7
	v_cvt_pk_bf16_f32 v243, v8, v9
	ds_write_b64 v55, v[242:243] offset:62560
	s_cbranch_scc1 .LBB0_483
	s_branch .LBB0_469
; __device__ __forceinline__ void ssd_scan_mfma(const Ctx& c, bf16* X2, const float* DT, const float* a_log, const float* dskip, bool do_store) {
;     ...
;             {
;                 const float csl = CS[16 * lt + l15];
;                 bf16x8 Cf[4];
; #pragma unroll
;                 for (int ks = 0; ks < 4; ++ks) Cf[ks] = *(const LAS bf16x8*)(L + SS_C + (16 * lt + l15) * 272 + (32 * ks + 8 * lg) * 2);
;                 f32x4 GT[4];
; #pragma unroll
;                 for (int st = 0; st < 4; ++st) { GT[st] = (f32x4){0.f, 0.f, 0.f, 0.f};
;                     if (st <= lt) {
; #pragma unroll
;                         for (int ks = 0; ks < 4; ++ks) { const bf16x8 bf = *(const LAS bf16x8*)(L + SS_B + (16 * st + l15) * 272 + (32 * ks + 8 * lg) * 2); GT[st] = __builtin_amdgcn_mfma_f32_16x16x32_bf16(bf, Cf[ks], GT[st], 0, 0, 0); }
;                         const f32x4 css = *(const LAS f32x4*)(CS + 16 * st + 4 * lg);
; #pragma unroll
;                         for (int r = 0; r < 4; ++r) { const bool ok = (16 * st + 4 * lg + r) <= (16 * lt + l15); GT[st][r] = ok ? GT[st][r] * __expf(csl - css[r]) : 0.f; }
;                     } }
;                 bf16x8 Lf[2];
; #pragma unroll
;                 for (int k2 = 0; k2 < 2; ++k2) { v4u q; q.x = pg8::cvt_pk_bf16(GT[2 * k2][0], GT[2 * k2][1]); q.y = pg8::cvt_pk_bf16(GT[2 * k2][2], GT[2 * k2][3]); q.z = pg8::cvt_pk_bf16(GT[2 * k2 + 1][0], GT[2 * k2 + 1][1]); q.w = pg8::cvt_pk_bf16(GT[2 * k2 + 1][2], GT[2 * k2 + 1][3]);
;                     Lf[k2] = __builtin_bit_cast(bf16x8, q); }
;                 const float el = __expf(csl);
;                 const LAS unsigned char* xdb = L + SS_XD + (4 * lg + tq) * 144 + tp * 8;
; #pragma unroll
;                 for (int pp = 0; pp < 2; ++pp) { const int pt = 2 * ph + pp; f32x4 Y = (f32x4){0.f, 0.f, 0.f, 0.f}, Yo = (f32x4){0.f, 0.f, 0.f, 0.f};
; #pragma unroll
;                     for (int k2 = 0; k2 < 2; ++k2) if (2 * k2 <= lt) { const LAS unsigned char* xp = xdb + k2 * 32 * 144 + pt * 32;
;                         Y = __builtin_amdgcn_mfma_f32_16x16x32_bf16(cat8(tr16(xp), tr16(xp + 16 * 144)), Lf[k2], Y, 0, 0, 0); }
; #pragma unroll
;                     for (int ks = 0; ks < 4; ++ks) { const bf16x8 sb = *(const LAS bf16x8*)(SBr + (16 * pt + l15) * 272 + (32 * ks + 8 * lg) * 2); Yo = __builtin_amdgcn_mfma_f32_16x16x32_bf16(sb, Cf[ks], Yo, 0, 0, 0); }
.Lmy_scan_lt1:
	ds_read_b32 v106, v69
	ds_read_b128 v[42:45], v139 offset:17408
	ds_read_b128 v[46:49], v139 offset:17472
	ds_read_b128 v[50:53], v139 offset:17536
	ds_read_b128 v[56:59], v139 offset:17600
	ds_read_b128 v[206:209], v133 offset:4352
	ds_read_b128 v[210:213], v133 offset:4416
	ds_read_b128 v[214:217], v133 offset:4480
	ds_read_b128 v[218:221], v133 offset:4544
	ds_read_b128 v[222:225], v141 offset:64
	s_mulk_i32 s96, 0x4400
	s_mulk_i32 s76, 0x4400
	s_add_u32 s10, s4, 0x23400000
	s_addc_u32 s11, s5, 0
	ds_read_b128 v[226:229], v133
	ds_read_b128 v[230:233], v133 offset:64
	ds_read_b128 v[234:237], v133 offset:128
	ds_read_b128 v[238:241], v133 offset:192
	ds_read_b128 v[242:245], v141
	v_add3_u32 v69, s96, v115, v120
	v_add3_u32 v107, s96, v115, v121
	v_add_u32_e32 v55, s76, v125
	s_waitcnt lgkmcnt(9)
	v_mfma_f32_16x16x32_bf16 v[206:209], v[206:209], v[42:45], 0
	s_waitcnt lgkmcnt(8)
	v_mfma_f32_16x16x32_bf16 v[206:209], v[210:213], v[46:49], v[206:209]
	s_waitcnt lgkmcnt(7)
	v_mfma_f32_16x16x32_bf16 v[206:209], v[214:217], v[50:53], v[206:209]
	s_waitcnt lgkmcnt(6)
	v_mfma_f32_16x16x32_bf16 v[206:209], v[218:221], v[56:59], v[206:209]
	ds_read_b64_tr_b16 v[60:61], v140 offset:44032
	ds_read_b64_tr_b16 v[62:63], v140 offset:46336
	s_waitcnt lgkmcnt(6)
	v_mfma_f32_16x16x32_bf16 v[226:229], v[226:229], v[42:45], 0
	s_waitcnt lgkmcnt(5)
	v_mfma_f32_16x16x32_bf16 v[226:229], v[230:233], v[46:49], v[226:229]
	s_waitcnt lgkmcnt(4)
	v_mfma_f32_16x16x32_bf16 v[226:229], v[234:237], v[50:53], v[226:229]
	s_waitcnt lgkmcnt(3)
	v_mfma_f32_16x16x32_bf16 v[226:229], v[238:241], v[56:59], v[226:229]
	ds_read_b64_tr_b16 v[142:143], v68 offset:44032
	ds_read_b64_tr_b16 v[144:145], v68 offset:46336
	v_sub_f32_e32 v222, v106, v222
	v_sub_f32_e32 v223, v106, v223
	v_sub_f32_e32 v224, v106, v224
	v_sub_f32_e32 v225, v106, v225
	v_mul_f32_e32 v222, 0x3fb8aa3b, v222
	v_mul_f32_e32 v223, 0x3fb8aa3b, v223
	v_mul_f32_e32 v224, 0x3fb8aa3b, v224
	v_mul_f32_e32 v225, 0x3fb8aa3b, v225
	v_exp_f32_e32 v222, v222
	v_exp_f32_e32 v223, v223
	v_exp_f32_e32 v224, v224
	v_exp_f32_e32 v225, v225
	v_mul_f32_e32 v206, v206, v222
	v_mul_f32_e32 v207, v207, v223
	v_mul_f32_e32 v208, v208, v224
	v_mul_f32_e32 v209, v209, v225
	v_cndmask_b32_e64 v206, v206, 0, s[24:25]
	v_cndmask_b32_e64 v207, v207, 0, s[26:27]
	v_cndmask_b32_e64 v208, v208, 0, s[28:29]
	v_cndmask_b32_e64 v209, v209, 0, s[30:31]
	ds_read_b128 v[150:153], v69 offset:62464
	ds_read_b128 v[154:157], v69 offset:62528
	ds_read_b128 v[158:161], v69 offset:62592
	ds_read_b128 v[246:249], v69 offset:62656
	ds_read_b64 v[162:163], v134 offset:34816
	s_waitcnt lgkmcnt(4)
	v_mfma_f32_16x16x32_bf16 v[150:153], v[150:153], v[42:45], 0
	s_waitcnt lgkmcnt(3)
	v_mfma_f32_16x16x32_bf16 v[150:153], v[154:157], v[46:49], v[150:153]
	s_waitcnt lgkmcnt(2)
	v_mfma_f32_16x16x32_bf16 v[150:153], v[158:161], v[50:53], v[150:153]
	s_waitcnt lgkmcnt(1)
	v_mfma_f32_16x16x32_bf16 v[150:153], v[246:249], v[56:59], v[150:153]
	v_sub_f32_e32 v242, v106, v242
	v_sub_f32_e32 v243, v106, v243
	v_sub_f32_e32 v244, v106, v244
	v_sub_f32_e32 v245, v106, v245
	v_mul_f32_e32 v242, 0x3fb8aa3b, v242
	v_mul_f32_e32 v243, 0x3fb8aa3b, v243
	v_mul_f32_e32 v244, 0x3fb8aa3b, v244
	v_mul_f32_e32 v245, 0x3fb8aa3b, v245
	v_exp_f32_e32 v242, v242
	v_exp_f32_e32 v243, v243
	v_exp_f32_e32 v244, v244
	v_exp_f32_e32 v245, v245
	v_mul_f32_e32 v226, v226, v242
	v_mul_f32_e32 v227, v227, v243
	v_mul_f32_e32 v228, v228, v244
	v_mul_f32_e32 v229, v229, v245
	v_cndmask_b32_e64 v226, v226, 0, s[16:17]
	v_cndmask_b32_e64 v227, 0, v227, s[18:19]
	v_cndmask_b32_e64 v228, v228, 0, s[20:21]
	v_cndmask_b32_e64 v229, v229, 0, s[22:23]
	v_mul_f32_e32 v106, 0x3fb8aa3b, v106
	v_exp_f32_e32 v106, v106
	v_cvt_pk_bf16_f32 v226, v226, v227
	v_cvt_pk_bf16_f32 v227, v228, v229
	v_cvt_pk_bf16_f32 v228, v206, v207
	v_cvt_pk_bf16_f32 v229, v208, v209
	v_mov_b32_e32 v168, s65
	ds_read_b128 v[170:173], v107 offset:62464
	ds_read_b128 v[174:177], v107 offset:62528
	ds_read_b128 v[178:181], v107 offset:62592
	ds_read_b128 v[182:185], v107 offset:62656
	ds_read_b64 v[166:167], v136 offset:34816
	ds_read_b32 v168, v168 offset:252
	v_lshl_add_u64 v[238:239], s[10:11], 0, v[98:99]
	v_mfma_f32_16x16x32_bf16 v[60:63], v[60:63], v[226:229], 0
	v_mfma_f32_16x16x32_bf16 v[142:145], v[142:145], v[226:229], 0
	s_waitcnt lgkmcnt(5)
	v_mfma_f32_16x16x32_bf16 v[170:173], v[170:173], v[42:45], 0
	s_waitcnt lgkmcnt(4)
	v_mfma_f32_16x16x32_bf16 v[170:173], v[174:177], v[46:49], v[170:173]
	s_waitcnt lgkmcnt(3)
	v_mfma_f32_16x16x32_bf16 v[170:173], v[178:181], v[50:53], v[170:173]
	s_waitcnt lgkmcnt(2)
	v_mfma_f32_16x16x32_bf16 v[170:173], v[182:185], v[56:59], v[170:173]
	ds_read_b64_tr_b16 v[190:191], v137 offset:53248
	ds_read_b64_tr_b16 v[192:193], v137 offset:53824
	ds_read_b64_tr_b16 v[194:195], v137 offset:57856
	ds_read_b64_tr_b16 v[196:197], v137 offset:58432
	ds_read_b64_tr_b16 v[198:199], v54
	ds_read_b64_tr_b16 v[200:201], v54 offset:1088
	ds_read_b64_tr_b16 v[202:203], v54 offset:8704
	ds_read_b64_tr_b16 v[204:205], v54 offset:9792
	s_waitcnt lgkmcnt(8)
	v_mul_f32_e32 v168, 0x3fb8aa3b, v168
	v_exp_f32_e32 v168, v168
	v_fma_f32 v60, v106, v150, v60
	v_fma_f32 v61, v106, v151, v61
	v_fma_f32 v62, v106, v152, v62
	v_fma_f32 v63, v106, v153, v63
	v_lshlrev_b32_e32 v150, 16, v162
	v_and_b32_e32 v151, 0xffff0000, v162
	v_lshlrev_b32_e32 v152, 16, v163
	v_and_b32_e32 v153, 0xffff0000, v163
	v_fma_f32 v60, v94, v150, v60
	v_fma_f32 v61, v94, v151, v61
	v_fma_f32 v62, v95, v152, v62
	v_fma_f32 v63, v95, v153, v63
	v_cvt_pk_bf16_f32 v162, v60, v61
	v_cvt_pk_bf16_f32 v163, v62, v63
	global_store_dwordx2 v[238:239], v[162:163], off
	v_pk_mul_f32 v[18:19], v[18:19], v[168:169] op_sel_hi:[1,0]
	v_pk_mul_f32 v[20:21], v[20:21], v[168:169] op_sel_hi:[1,0]
	v_pk_mul_f32 v[14:15], v[14:15], v[168:169] op_sel_hi:[1,0]
	v_pk_mul_f32 v[16:17], v[16:17], v[168:169] op_sel_hi:[1,0]
	v_pk_mul_f32 v[10:11], v[10:11], v[168:169] op_sel_hi:[1,0]
	v_pk_mul_f32 v[12:13], v[12:13], v[168:169] op_sel_hi:[1,0]
	v_pk_mul_f32 v[6:7], v[6:7], v[168:169] op_sel_hi:[1,0]
	v_pk_mul_f32 v[8:9], v[8:9], v[168:169] op_sel_hi:[1,0]
	s_waitcnt lgkmcnt(2)
; #define LAS __attribute__((address_space(3)))
; __device__ __forceinline__ void ssd_scan_mfma(const Ctx& c, bf16* X2, const float* DT, const float* a_log, const float* dskip, bool do_store) {
;     ...
;             {
;                 const float csl = CS[16 * lt + l15];
;                 bf16x8 Cf[4];
; #pragma unroll
;                 for (int ks = 0; ks < 4; ++ks) Cf[ks] = *(const LAS bf16x8*)(L + SS_C + (16 * lt + l15) * 272 + (32 * ks + 8 * lg) * 2);
;                 f32x4 GT[4];
; #pragma unroll
;                 for (int st = 0; st < 4; ++st) { GT[st] = (f32x4){0.f, 0.f, 0.f, 0.f};
;                     if (st <= lt) {
; #pragma unroll
;     ...
;                     for (int ks = 0; ks < 4; ++ks) { const bf16x8 sb = *(const LAS bf16x8*)(SBr + (16 * pt + l15) * 272 + (32 * ks + 8 * lg) * 2); Yo = __builtin_amdgcn_mfma_f32_16x16x32_bf16(sb, Cf[ks], Yo, 0, 0, 0); }
;                     const v2u xr = *(const LAS v2u*)(L + SS_XR + (16 * lt + l15) * 144 + (16 * pt + 4 * lg) * 2);
;                     const float y0 = Y[0] + el * Yo[0] + Dh * bflo(xr.x), y1 = Y[1] + el * Yo[1] + Dh * bfhi(xr.x), y2 = Y[2] + el * Yo[2] + Dh * bflo(xr.y), y3 = Y[3] + el * Yo[3] + Dh * bfhi(xr.y);
;                     v2u o; o.x = pk2(y0, y1); o.y = pk2(y2, y3);
;                     if (do_store) *(v2u*)(X2 + ((size_t)b * SEQ + t0 + 16 * lt + l15) * 6144 + h * 64 + 16 * pt + 4 * lg) = o; }
;                 const float e63 = __expf(CS[63]); const int pts = w >> 1;
;                 const LAS unsigned char* bb = L + SS_B + (8 * lg + tq) * 272 + tp * 8; const LAS unsigned char* xwb = L + SS_XW + (8 * lg + tq) * 144 + tp * 8 + pts * 32;
;                 bf16x8 Xf[2];
; #pragma unroll
;                 for (int ks = 0; ks < 2; ++ks) Xf[ks] = cat8(tr16(xwb + ks * 32 * 144), tr16(xwb + ks * 32 * 144 + 4 * 144));
; #pragma unroll
;                 for (int i = 0; i < 4; ++i) { const int nt = 4 * (w & 1) + i; ST[i] *= e63;
; #pragma unroll
;                     for (int ks = 0; ks < 2; ++ks) { const LAS unsigned char* bp = bb + ks * 32 * 272 + nt * 32;
;                         ST[i] = __builtin_amdgcn_mfma_f32_16x16x32_bf16(cat8(tr16(bp), tr16(bp + 4 * 272)), Xf[ks], ST[i], 0, 0, 0); }
;                     v2u q; q.x = pk2(ST[i][0], ST[i][1]); q.y = pk2(ST[i][2], ST[i][3]);
;                     *(LAS v2u*)(SBw + (16 * pts + l15) * 272 + (16 * nt + 4 * lg) * 2) = q; }
	v_mfma_f32_16x16x32_bf16 v[18:21], v[198:201], v[190:193], v[18:21]
	s_waitcnt lgkmcnt(0)
	v_mfma_f32_16x16x32_bf16 v[18:21], v[202:205], v[194:197], v[18:21]
	ds_read_b64_tr_b16 v[210:211], v54 offset:32
	ds_read_b64_tr_b16 v[212:213], v54 offset:1120
	ds_read_b64_tr_b16 v[214:215], v54 offset:8736
	ds_read_b64_tr_b16 v[216:217], v54 offset:9824
	v_fma_f32 v142, v106, v170, v142
	v_fma_f32 v143, v106, v171, v143
	v_fma_f32 v144, v106, v172, v144
	v_fma_f32 v145, v106, v173, v145
	v_lshlrev_b32_e32 v170, 16, v166
	v_and_b32_e32 v171, 0xffff0000, v166
	v_lshlrev_b32_e32 v172, 16, v167
	v_and_b32_e32 v173, 0xffff0000, v167
	v_fma_f32 v142, v94, v170, v142
	v_fma_f32 v143, v94, v171, v143
	v_fma_f32 v144, v95, v172, v144
	v_fma_f32 v145, v95, v173, v145
	v_cvt_pk_bf16_f32 v166, v142, v143
	v_cvt_pk_bf16_f32 v167, v144, v145
	global_store_dwordx2 v[238:239], v[166:167], off offset:32
	s_waitcnt lgkmcnt(2)
	v_mfma_f32_16x16x32_bf16 v[14:17], v[210:213], v[190:193], v[14:17]
	s_waitcnt lgkmcnt(0)
	v_mfma_f32_16x16x32_bf16 v[14:17], v[214:217], v[194:197], v[14:17]
	ds_read_b64_tr_b16 v[218:219], v54 offset:64
	ds_read_b64_tr_b16 v[220:221], v54 offset:1152
	ds_read_b64_tr_b16 v[222:223], v54 offset:8768
	ds_read_b64_tr_b16 v[224:225], v54 offset:9856
	v_cvt_pk_bf16_f32 v240, v18, v19
	v_cvt_pk_bf16_f32 v241, v20, v21
	ds_write_b64 v55, v[240:241] offset:62464
	s_waitcnt lgkmcnt(3)
	v_mfma_f32_16x16x32_bf16 v[10:13], v[218:221], v[190:193], v[10:13]
	s_waitcnt lgkmcnt(1)
	v_mfma_f32_16x16x32_bf16 v[10:13], v[222:225], v[194:197], v[10:13]
	ds_read_b64_tr_b16 v[230:231], v54 offset:96
	ds_read_b64_tr_b16 v[232:233], v54 offset:1184
	ds_read_b64_tr_b16 v[234:235], v54 offset:8800
	ds_read_b64_tr_b16 v[236:237], v54 offset:9888
	v_cvt_pk_bf16_f32 v242, v14, v15
	v_cvt_pk_bf16_f32 v243, v16, v17
	ds_write_b64 v55, v[242:243] offset:62496
	s_waitcnt lgkmcnt(3)
	v_mfma_f32_16x16x32_bf16 v[6:9], v[230:233], v[190:193], v[6:9]
	s_waitcnt lgkmcnt(1)
	v_mfma_f32_16x16x32_bf16 v[6:9], v[234:237], v[194:197], v[6:9]
	s_mov_b64 s[96:97], 0x4000
	s_add_i32 s63, s63, 1
	v_lshl_add_u64 v[96:97], v[96:97], 0, s[96:97]
	v_lshl_add_u64 v[98:99], v[98:99], 0, s[58:59]
	v_lshl_add_u64 v[100:101], v[100:101], 0, s[58:59]
	v_lshl_add_u64 v[102:103], v[102:103], 0, s[58:59]
	v_lshl_add_u64 v[104:105], v[104:105], 0, s[58:59]
	v_cvt_pk_bf16_f32 v240, v10, v11
	v_cvt_pk_bf16_f32 v241, v12, v13
	ds_write_b64 v55, v[240:241] offset:62528
	s_cmp_eq_u32 s63, 63
	v_cvt_pk_bf16_f32 v242, v6, v7
	v_cvt_pk_bf16_f32 v243, v8, v9
	ds_write_b64 v55, v[242:243] offset:62560
	s_cbranch_scc1 .LBB0_483
	s_branch .LBB0_469
.Lmy_scan_lt0:
	ds_read_b32 v106, v69
	ds_read_b128 v[42:45], v139 offset:17408
	ds_read_b128 v[46:49], v139 offset:17472
	ds_read_b128 v[50:53], v139 offset:17536
	ds_read_b128 v[56:59], v139 offset:17600
	ds_read_b128 v[226:229], v133
	ds_read_b128 v[230:233], v133 offset:64
	ds_read_b128 v[234:237], v133 offset:128
	ds_read_b128 v[238:241], v133 offset:192
	ds_read_b128 v[242:245], v141
	s_mulk_i32 s96, 0x4400
	s_mulk_i32 s76, 0x4400
	s_add_u32 s10, s4, 0x23400000
	s_addc_u32 s11, s5, 0
	ds_read_b64_tr_b16 v[60:61], v140 offset:44032
	ds_read_b64_tr_b16 v[62:63], v140 offset:46336
	v_add3_u32 v69, s96, v115, v120
	v_add3_u32 v107, s96, v115, v121
	v_add_u32_e32 v55, s76, v125
	s_waitcnt lgkmcnt(6)
	v_mfma_f32_16x16x32_bf16 v[226:229], v[226:229], v[42:45], 0
	s_waitcnt lgkmcnt(5)
	v_mfma_f32_16x16x32_bf16 v[226:229], v[230:233], v[46:49], v[226:229]
	s_waitcnt lgkmcnt(4)
	v_mfma_f32_16x16x32_bf16 v[226:229], v[234:237], v[50:53], v[226:229]
	s_waitcnt lgkmcnt(3)
	v_mfma_f32_16x16x32_bf16 v[226:229], v[238:241], v[56:59], v[226:229]
	ds_read_b64_tr_b16 v[142:143], v68 offset:44032
	ds_read_b64_tr_b16 v[144:145], v68 offset:46336
	ds_read_b128 v[150:153], v69 offset:62464
	ds_read_b128 v[154:157], v69 offset:62528
	ds_read_b128 v[158:161], v69 offset:62592
	ds_read_b128 v[246:249], v69 offset:62656
	ds_read_b64 v[162:163], v134 offset:34816
	s_waitcnt lgkmcnt(4)
	v_mfma_f32_16x16x32_bf16 v[150:153], v[150:153], v[42:45], 0
	s_waitcnt lgkmcnt(3)
	v_mfma_f32_16x16x32_bf16 v[150:153], v[154:157], v[46:49], v[150:153]
	s_waitcnt lgkmcnt(2)
	v_mfma_f32_16x16x32_bf16 v[150:153], v[158:161], v[50:53], v[150:153]
	s_waitcnt lgkmcnt(1)
	v_mfma_f32_16x16x32_bf16 v[150:153], v[246:249], v[56:59], v[150:153]
	v_sub_f32_e32 v242, v106, v242
	v_sub_f32_e32 v243, v106, v243
	v_sub_f32_e32 v244, v106, v244
	v_sub_f32_e32 v245, v106, v245
	v_mul_f32_e32 v242, 0x3fb8aa3b, v242
	v_mul_f32_e32 v243, 0x3fb8aa3b, v243
	v_mul_f32_e32 v244, 0x3fb8aa3b, v244
	v_mul_f32_e32 v245, 0x3fb8aa3b, v245
	v_exp_f32_e32 v242, v242
	v_exp_f32_e32 v243, v243
	v_exp_f32_e32 v244, v244
	v_exp_f32_e32 v245, v245
	v_mul_f32_e32 v226, v226, v242
	v_mul_f32_e32 v227, v227, v243
	v_mul_f32_e32 v228, v228, v244
	v_mul_f32_e32 v229, v229, v245
	v_cndmask_b32_e64 v226, v226, 0, s[16:17]
	v_cndmask_b32_e64 v227, 0, v227, s[18:19]
	v_cndmask_b32_e64 v228, v228, 0, s[20:21]
	v_cndmask_b32_e64 v229, v229, 0, s[22:23]
	v_mul_f32_e32 v106, 0x3fb8aa3b, v106
	v_exp_f32_e32 v106, v106
	v_cvt_pk_bf16_f32 v226, v226, v227
	v_cvt_pk_bf16_f32 v227, v228, v229
	v_mov_b32_e32 v228, 0
	v_mov_b32_e32 v229, 0
	v_mov_b32_e32 v168, s65
	ds_read_b128 v[170:173], v107 offset:62464
	ds_read_b128 v[174:177], v107 offset:62528
	ds_read_b128 v[178:181], v107 offset:62592
	ds_read_b128 v[182:185], v107 offset:62656
	ds_read_b64 v[166:167], v136 offset:34816
	ds_read_b32 v168, v168 offset:252
	v_lshl_add_u64 v[238:239], s[10:11], 0, v[98:99]
	v_mfma_f32_16x16x32_bf16 v[60:63], v[60:63], v[226:229], 0
	v_mfma_f32_16x16x32_bf16 v[142:145], v[142:145], v[226:229], 0
	s_waitcnt lgkmcnt(5)
; #define LAS __attribute__((address_space(3)))
; __device__ __forceinline__ unsigned pk2(float lo, float hi) { return f2bf(lo) | (f2bf(hi) << 16); }
; __device__ __forceinline__ s16x4 tr16(const LAS unsigned char* p) { return __builtin_amdgcn_ds_read_tr16_b64_v4i16((LAS s16x4*)p); }
; __device__ __forceinline__ void ssd_scan_mfma(const Ctx& c, bf16* X2, const float* DT, const float* a_log, const float* dskip, bool do_store) {
;     ...
;                     for (int ks = 0; ks < 4; ++ks) { const bf16x8 sb = *(const LAS bf16x8*)(SBr + (16 * pt + l15) * 272 + (32 * ks + 8 * lg) * 2); Yo = __builtin_amdgcn_mfma_f32_16x16x32_bf16(sb, Cf[ks], Yo, 0, 0, 0); }
;                     const v2u xr = *(const LAS v2u*)(L + SS_XR + (16 * lt + l15) * 144 + (16 * pt + 4 * lg) * 2);
;                     const float y0 = Y[0] + el * Yo[0] + Dh * bflo(xr.x), y1 = Y[1] + el * Yo[1] + Dh * bfhi(xr.x), y2 = Y[2] + el * Yo[2] + Dh * bflo(xr.y), y3 = Y[3] + el * Yo[3] + Dh * bfhi(xr.y);
;                     v2u o; o.x = pk2(y0, y1); o.y = pk2(y2, y3);
;                     if (do_store) *(v2u*)(X2 + ((size_t)b * SEQ + t0 + 16 * lt + l15) * 6144 + h * 64 + 16 * pt + 4 * lg) = o; }
;                 const float e63 = __expf(CS[63]); const int pts = w >> 1;
;                 const LAS unsigned char* bb = L + SS_B + (8 * lg + tq) * 272 + tp * 8; const LAS unsigned char* xwb = L + SS_XW + (8 * lg + tq) * 144 + tp * 8 + pts * 32;
;                 bf16x8 Xf[2];
; #pragma unroll
;                 for (int ks = 0; ks < 2; ++ks) Xf[ks] = cat8(tr16(xwb + ks * 32 * 144), tr16(xwb + ks * 32 * 144 + 4 * 144));
; #pragma unroll
;                 for (int i = 0; i < 4; ++i) { const int nt = 4 * (w & 1) + i; ST[i] *= e63;
; #pragma unroll
;                     for (int ks = 0; ks < 2; ++ks) { const LAS unsigned char* bp = bb + ks * 32 * 272 + nt * 32;
;                         ST[i] = __builtin_amdgcn_mfma_f32_16x16x32_bf16(cat8(tr16(bp), tr16(bp + 4 * 272)), Xf[ks], ST[i], 0, 0, 0); }
;                     v2u q; q.x = pk2(ST[i][0], ST[i][1]); q.y = pk2(ST[i][2], ST[i][3]);
;                     *(LAS v2u*)(SBw + (16 * pts + l15) * 272 + (16 * nt + 4 * lg) * 2) = q; }
	v_mfma_f32_16x16x32_bf16 v[170:173], v[170:173], v[42:45], 0
	s_waitcnt lgkmcnt(4)
	v_mfma_f32_16x16x32_bf16 v[170:173], v[174:177], v[46:49], v[170:173]
	s_waitcnt lgkmcnt(3)
	v_mfma_f32_16x16x32_bf16 v[170:173], v[178:181], v[50:53], v[170:173]
	s_waitcnt lgkmcnt(2)
	v_mfma_f32_16x16x32_bf16 v[170:173], v[182:185], v[56:59], v[170:173]
	ds_read_b64_tr_b16 v[190:191], v137 offset:53248
	ds_read_b64_tr_b16 v[192:193], v137 offset:53824
	ds_read_b64_tr_b16 v[194:195], v137 offset:57856
	ds_read_b64_tr_b16 v[196:197], v137 offset:58432
	ds_read_b64_tr_b16 v[198:199], v54
	ds_read_b64_tr_b16 v[200:201], v54 offset:1088
	ds_read_b64_tr_b16 v[202:203], v54 offset:8704
	ds_read_b64_tr_b16 v[204:205], v54 offset:9792
	s_waitcnt lgkmcnt(8)
	v_mul_f32_e32 v168, 0x3fb8aa3b, v168
	v_exp_f32_e32 v168, v168
	v_fma_f32 v60, v106, v150, v60
	v_fma_f32 v61, v106, v151, v61
	v_fma_f32 v62, v106, v152, v62
	v_fma_f32 v63, v106, v153, v63
	v_lshlrev_b32_e32 v150, 16, v162
	v_and_b32_e32 v151, 0xffff0000, v162
	v_lshlrev_b32_e32 v152, 16, v163
	v_and_b32_e32 v153, 0xffff0000, v163
	v_fma_f32 v60, v94, v150, v60
	v_fma_f32 v61, v94, v151, v61
	v_fma_f32 v62, v95, v152, v62
	v_fma_f32 v63, v95, v153, v63
	v_cvt_pk_bf16_f32 v162, v60, v61
	v_cvt_pk_bf16_f32 v163, v62, v63
	global_store_dwordx2 v[238:239], v[162:163], off
	v_pk_mul_f32 v[18:19], v[18:19], v[168:169] op_sel_hi:[1,0]
	v_pk_mul_f32 v[20:21], v[20:21], v[168:169] op_sel_hi:[1,0]
	v_pk_mul_f32 v[14:15], v[14:15], v[168:169] op_sel_hi:[1,0]
	v_pk_mul_f32 v[16:17], v[16:17], v[168:169] op_sel_hi:[1,0]
	v_pk_mul_f32 v[10:11], v[10:11], v[168:169] op_sel_hi:[1,0]
	v_pk_mul_f32 v[12:13], v[12:13], v[168:169] op_sel_hi:[1,0]
	v_pk_mul_f32 v[6:7], v[6:7], v[168:169] op_sel_hi:[1,0]
	v_pk_mul_f32 v[8:9], v[8:9], v[168:169] op_sel_hi:[1,0]
	s_waitcnt lgkmcnt(2)
	v_mfma_f32_16x16x32_bf16 v[18:21], v[198:201], v[190:193], v[18:21]
	s_waitcnt lgkmcnt(0)
	v_mfma_f32_16x16x32_bf16 v[18:21], v[202:205], v[194:197], v[18:21]
	ds_read_b64_tr_b16 v[210:211], v54 offset:32
	ds_read_b64_tr_b16 v[212:213], v54 offset:1120
	ds_read_b64_tr_b16 v[214:215], v54 offset:8736
	ds_read_b64_tr_b16 v[216:217], v54 offset:9824
	v_fma_f32 v142, v106, v170, v142
	v_fma_f32 v143, v106, v171, v143
	v_fma_f32 v144, v106, v172, v144
	v_fma_f32 v145, v106, v173, v145
	v_lshlrev_b32_e32 v170, 16, v166
	v_and_b32_e32 v171, 0xffff0000, v166
	v_lshlrev_b32_e32 v172, 16, v167
	v_and_b32_e32 v173, 0xffff0000, v167
	v_fma_f32 v142, v94, v170, v142
	v_fma_f32 v143, v94, v171, v143
	v_fma_f32 v144, v95, v172, v144
	v_fma_f32 v145, v95, v173, v145
	v_cvt_pk_bf16_f32 v166, v142, v143
	v_cvt_pk_bf16_f32 v167, v144, v145
	global_store_dwordx2 v[238:239], v[166:167], off offset:32
	s_waitcnt lgkmcnt(2)
	v_mfma_f32_16x16x32_bf16 v[14:17], v[210:213], v[190:193], v[14:17]
	s_waitcnt lgkmcnt(0)
	v_mfma_f32_16x16x32_bf16 v[14:17], v[214:217], v[194:197], v[14:17]
	ds_read_b64_tr_b16 v[218:219], v54 offset:64
	ds_read_b64_tr_b16 v[220:221], v54 offset:1152
	ds_read_b64_tr_b16 v[222:223], v54 offset:8768
	ds_read_b64_tr_b16 v[224:225], v54 offset:9856
	v_cvt_pk_bf16_f32 v240, v18, v19
	v_cvt_pk_bf16_f32 v241, v20, v21
	ds_write_b64 v55, v[240:241] offset:62464
	s_waitcnt lgkmcnt(3)
	v_mfma_f32_16x16x32_bf16 v[10:13], v[218:221], v[190:193], v[10:13]
	s_waitcnt lgkmcnt(1)
	v_mfma_f32_16x16x32_bf16 v[10:13], v[222:225], v[194:197], v[10:13]
	ds_read_b64_tr_b16 v[230:231], v54 offset:96
	ds_read_b64_tr_b16 v[232:233], v54 offset:1184
	ds_read_b64_tr_b16 v[234:235], v54 offset:8800
	ds_read_b64_tr_b16 v[236:237], v54 offset:9888
	v_cvt_pk_bf16_f32 v242, v14, v15
	v_cvt_pk_bf16_f32 v243, v16, v17
	ds_write_b64 v55, v[242:243] offset:62496
	s_waitcnt lgkmcnt(3)
	v_mfma_f32_16x16x32_bf16 v[6:9], v[230:233], v[190:193], v[6:9]
	s_waitcnt lgkmcnt(1)
	v_mfma_f32_16x16x32_bf16 v[6:9], v[234:237], v[194:197], v[6:9]
	s_mov_b64 s[96:97], 0x4000
	s_add_i32 s63, s63, 1
	v_lshl_add_u64 v[96:97], v[96:97], 0, s[96:97]
	v_lshl_add_u64 v[98:99], v[98:99], 0, s[58:59]
	v_lshl_add_u64 v[100:101], v[100:101], 0, s[58:59]
	v_lshl_add_u64 v[102:103], v[102:103], 0, s[58:59]
	v_lshl_add_u64 v[104:105], v[104:105], 0, s[58:59]
	v_cvt_pk_bf16_f32 v240, v10, v11
	v_cvt_pk_bf16_f32 v241, v12, v13
	ds_write_b64 v55, v[240:241] offset:62528
	s_cmp_eq_u32 s63, 63
	v_cvt_pk_bf16_f32 v242, v6, v7
	v_cvt_pk_bf16_f32 v243, v8, v9
	ds_write_b64 v55, v[242:243] offset:62560
	s_cbranch_scc0 .LBB0_469
